# compress-before-in-proj split by block-index bit 0 (whole XCDs stream while the other XCDs run the GEMM, then swap) instead of bit 3 (both kinds on every XCD)
# baseline (speedup 1.0000x reference)
; #define LAS __attribute__((address_space(3)))
; template <class Tp> DEV Tp* wsp(const Frame& F, size_t off) { return (Tp*)(F.ws + off); }
; #define PHASE_BEGIN() do { int t_ = threadIdx.x; asm volatile("" : "+v"(t_)); F.tid = t_; F.lane = t_ & 63; F.wave = __builtin_amdgcn_readfirstlane(t_ >> 6); } while (0)
; __global__ void __launch_bounds__(512, 2) mk_fwd(Args args) {
;     ...
;     if (IN(1)) {
;         SchedOne S{(const char*)(F.ws + WS_XN), (const char*)(F.ws + WS_WIN), MP / 256, NIN / 256, 1024, F.G, cid};
;         EpiP1 E{F.out, wsp<bf16>(F, WS_QA), wsp<bf16>(F, WS_KS), wsp<bf16>(F, WS_VS), wsp<bf16>(F, WS_KW), wsp<bf16>(F, WS_VW), wsp<bf16>(F, WS_CKP), wsp<bf16>(F, WS_CVP), wsp<bf16>(F, WS_HQ), wsp<bf16>(F, WS_HI),
;                 wsp<bf16>(F, WS_HG), wsp<bf16>(F, WS_SGA), wsp<bf16>(F, WS_SGB), wsp<bf16>(F, WS_TK), wsp<bf16>(F, WS_TV), wsp<float>(F, WS_HF), wsp<float>(F, WS_GA)};
;         pg8::gemm_phase<EpiP1, SchedOne, true, true>(F.lds, 1024, S, E);
;         if (PROBE_REP & (1 << 1)) {pg8::gemm_phase<EpiP1, SchedOne, true, true>(F.lds, 1024, S, E); }
;         PHASE_BEGIN();
;         { LAS float* scr = (LAS float*)(F.lds + F.wave * 16384);
;           const int rem = P1_U0 % F.G, first = rem ? rem : 0, nw = (F.G - first) * 8;
;           if (cid >= first) for (int d = (cid - first) * 8 + F.wave; d < DEF_N; d += nw) { if (d < DEF_NTR) tr_dispatch(F, DEF_I0 + d, scr, F.lane); else win_copy_item(F, d - DEF_NTR, F.lane); }
;           __syncthreads(); }
;         for (int rep = 0; rep < ((PROBE_REP >> 14) & 1) + 1; ++rep)
;         for (int u = F.G - 1 - F.vcu; u < 512; u += F.G) cmp_gemm_unit(F, u >> 8, u & 255);
.Lmy_p1_entry:
	s_cmp_lg_u32 s98, 0
	s_cbranch_scc1 .Lmy_p1_go
	s_bitcmp1_b32 s92, 0
	s_cbranch_scc0 .Lmy_p1_go
	s_mov_b32 s98, 1
	v_mov_b32_e32 v1, v0
	v_and_b32_e32 v210, 63, v0
	s_nop 0
	v_readfirstlane_b32 s14, v1
	s_nop 3
	s_ashr_i32 s14, s14, 6
	s_branch .LBB0_651
